# EpiMla rope-table address slices hoisted so rope loads overlap the per-block reduction
# speedup vs baseline: 1.0772x; 1.0023x over previous
; #define PIN(i) ((const float*)(const GASP float*)karg_q(i))
;     __device__ __forceinline__ void operator()(const f32x4 (&acc)[2][2][4][2], const Unit& u, int wr, int wc, int, int) const {
;         const int lane_ = ::otid() & 63, fr = lane_ & 15, fq = lane_ >> 4;
;         unsigned char* ws = PWS;
;         const bool isq = u.pn < 3; const int head = (isq ? u.pn : u.pn - 3) * 2 + (wc >> 1), kind = wc & 1;
;         const bool latent = u.pm < 128, is_v = !isq && kind == 1, is_rope = isq && kind == 1, rot = is_rope && latent;
;         const int sbj = is_rope ? 8 : 32;
;         const float* gsrc = is_v ? (const float*)(ws + WS_ROPE) + 1024 : (isq ? PIN(16) + l * 96 : PIN(17) + l * 96);
;         const float* g = gsrc + (is_rope ? 64 + 16 * (fq & 1) : 8 * fq);
;         const float* rope = (const float*)(ws + WS_ROPE);
;         bf16_t* obase = (bf16_t*)(ws + (is_v ? WS_MV : (isq ? WS_MQ : WS_MK)));
;         const int ostride = is_v ? 384 : 576;
;         const int ocol = is_v ? head * 64 + 8 * fq : head * 96 + (is_rope ? 64 + 16 * (fq & 1) : 8 * fq);
;         const float inv_cnt = is_rope ? (1.0f / 32.0f) : (1.0f / 64.0f), sc = isq ? MLA_SCALE : 1.0f;
;         const bool st_ok = !is_rope || fq < 2;
;         const int rowb = u.pm * BM + wr * 64 + fr;
; #pragma unroll
;         for (int ai = 0; ai < 2; ++ai)
; #pragma unroll
;             for (int m = 0; m < 4; ++m) {
;                 const int row = rowb + ai * HALF + m * 16;
;                 float ss = 0.f;
; #pragma unroll
;                 for (int j = 0; j < 4; ++j) ss += acc[ai][0][m][0][j] * acc[ai][0][m][0][j] + acc[ai][0][m][1][j] * acc[ai][0][m][1][j] + acc[ai][1][m][0][j] * acc[ai][1][m][0][j] + acc[ai][1][m][1][j] * acc[ai][1][m][1][j];
;                 ss += ::swz<16>(ss); ss = ::x32_sum(ss);
;                 float rs = rsqrtf(ss * inv_cnt + 1e-6f) * sc; rs = is_v ? 1.0f : rs;
;                 const int pos = row & 2047, pp = rot ? ((fq & 1) ? (pos & 63) : (pos >> 6)) : 0;
;                 const float* rt = rope + pp * 16;
;                 bf16_t* dst = obase + (unsigned)(row * ostride + ocol);
; #pragma unroll
;                 for (int n = 0; n < 2; ++n) {
;                     const f32x4 g1 = *(const f32x4*)(g + 4 * n), g2 = *(const f32x4*)(g + sbj + 4 * n);
;                     const f32x4 t0 = *(const f32x4*)(rt + 8 * n), t1 = *(const f32x4*)(rt + 8 * n + 4);
.LBB0_669:
	v_and_b32_e32 v161, 15, v140
	v_mov_b32_e32 v140, 0x3c800000
	v_mov_b32_e32 v143, 0x3d000000
	v_lshlrev_b32_e32 v138, 2, v138
	v_mov_b32_e32 v139, v0
	v_cndmask_b32_e64 v159, v140, v143, s[42:43]
	v_mov_b32_e32 v140, 0x3e16c740
	v_lshl_add_u64 v[138:139], s[2:3], 0, v[138:139]
	global_load_dwordx4 v[172:175], v[138:139], off
	s_and_b64 s[2:3], s[40:41], exec
	v_cndmask_b32_e64 v143, 1.0, v140, s[40:41]
	v_cmp_gt_u32_e64 s[40:41], 2, v141
	v_mul_f32_e32 v140, v118, v118
	v_mul_f32_e32 v141, v119, v119
	v_fmac_f32_e32 v140, v126, v126
	v_fmac_f32_e32 v141, v127, v127
	v_fmac_f32_e32 v140, v122, v122
	v_fmac_f32_e32 v141, v123, v123
	v_fmac_f32_e32 v140, v114, v114
	v_fmac_f32_e32 v141, v115, v115
	v_add_f32_e32 v140, v140, v141
	v_mul_f32_e32 v141, v120, v120
	v_fmac_f32_e32 v141, v128, v128
	s_cselect_b32 s3, 0x16b98000, s76
	v_fmac_f32_e32 v141, v124, v124
	s_cselect_b32 s2, 0, 0
	s_add_u32 s60, s56, s3
	v_fmac_f32_e32 v141, v116, v116
	s_addc_u32 s61, s57, s2
	v_add_f32_e32 v140, v141, v140
	v_mul_f32_e32 v141, v121, v121
	s_cmpk_lt_i32 s54, 0x80
	v_fmac_f32_e32 v141, v129, v129
	s_cselect_b64 s[2:3], -1, 0
	v_fmac_f32_e32 v141, v125, v125
	s_and_b64 vcc, s[42:43], s[2:3]
	s_xor_b64 s[2:3], s[42:43], -1
	v_fmac_f32_e32 v141, v117, v117
	s_or_b64 s[20:21], s[2:3], s[40:41]
	v_cmp_eq_u32_e64 s[40:41], 0, v144
	v_add_f32_e32 v144, v141, v140
	ds_swizzle_b32 v145, v144 offset:swizzle(SWAP,16)
	s_lshl_b32 s2, s54, 8
	s_add_i32 s5, s2, s78
	s_and_b64 s[2:3], s[42:43], exec
	s_cselect_b32 s16, 8, 32
	s_waitcnt lgkmcnt(0)
	v_add_f32_e32 v158, v144, v145
	s_lshl_b32 s54, s16, 2
	v_mov_b32_e32 v162, v158
	v_or_b32_e32 v160, s5, v161
	v_lshl_add_u64 v[140:141], v[138:139], 0, s[54:55]
	s_bfe_u32 s17, s5, 0x50006
	v_mov_b32_e32 v248, s17
	v_cndmask_b32_e64 v248, v161, v248, s[40:41]
	v_lshlrev_b32_e32 v248, 4, v248
	v_cndmask_b32_e32 v248, 0, v248, vcc
	v_lshlrev_b32_e32 v249, 2, v248
	global_load_dwordx4 v[176:179], v249, s[22:23]
	global_load_dwordx4 v[180:183], v249, s[22:23] offset:16
	global_load_dwordx4 v[184:187], v[140:141], off
	global_load_dwordx4 v[188:191], v[138:139], off offset:16
	global_load_dwordx4 v[192:195], v249, s[22:23] offset:32
	global_load_dwordx4 v[196:199], v249, s[22:23] offset:48
	global_load_dwordx4 v[200:203], v[140:141], off offset:16
	v_permlane32_swap_b32_e32 v158, v162
	s_and_saveexec_b64 s[2:3], s[20:21]
	v_add_f32_e32 v146, v158, v162
	v_mad_u64_u32 v[144:145], s[42:43], s26, v160, v[142:143]
	v_fmaak_f32 v146, v159, v146, 0x358637bd
	v_cmp_gt_f32_e64 s[42:43], s88, v146
	v_mul_f32_e32 v147, 0x4b800000, v146
	v_mov_b32_e32 v145, v0
	v_cndmask_b32_e64 v146, v146, v147, s[42:43]
	v_rsq_f32_e32 v146, v146
	v_lshl_add_u64 v[156:157], v[144:145], 1, s[60:61]
	s_lshl_b32 s54, s16, 1
	v_lshl_add_u64 v[144:145], v[156:157], 0, s[54:55]
	v_mul_f32_e32 v147, 0x45800000, v146
	v_cndmask_b32_e64 v146, v146, v147, s[42:43]
	v_mul_f32_e32 v146, v143, v146
	v_cndmask_b32_e64 v158, v146, 1.0, s[50:51]
	v_pk_mul_f32 v[146:147], v[128:129], v[158:159] op_sel_hi:[1,0]
	v_pk_mul_f32 v[148:149], v[126:127], v[158:159] op_sel_hi:[1,0]
	global_load_dwordx4 v[204:207], v[138:139], off
	v_pk_mul_f32 v[150:151], v[122:123], v[158:159] op_sel_hi:[1,0]
	v_pk_mul_f32 v[152:153], v[124:125], v[158:159] op_sel_hi:[1,0]
	s_waitcnt vmcnt(8)
	v_pk_mul_f32 v[148:149], v[148:149], v[172:173]
	v_pk_mul_f32 v[146:147], v[146:147], v[174:175]
	s_waitcnt vmcnt(6)
	v_mov_b32_e32 v166, v180
	s_waitcnt vmcnt(5)
	v_pk_mul_f32 v[124:125], v[152:153], v[186:187]
	v_pk_mul_f32 v[122:123], v[150:151], v[184:185]
	v_mov_b32_e32 v150, v176
	v_mov_b32_e32 v151, v178
	v_mov_b32_e32 v167, v182
	v_mov_b32_e32 v182, v181
	v_mov_b32_e32 v178, v177
	v_pk_mul_f32 v[152:153], v[150:151], v[122:123]
	v_pk_mul_f32 v[168:169], v[166:167], v[124:125]
	v_pk_mul_f32 v[122:123], v[178:179], v[122:123]
	v_pk_mul_f32 v[124:125], v[182:183], v[124:125]
	v_pk_fma_f32 v[122:123], v[148:149], v[150:151], v[122:123] neg_lo:[0,0,1] neg_hi:[0,0,1]
	v_pk_fma_f32 v[124:125], v[146:147], v[166:167], v[124:125] neg_lo:[0,0,1] neg_hi:[0,0,1]
	v_pk_fma_f32 v[162:163], v[146:147], v[182:183], v[168:169]
	v_pk_fma_f32 v[126:127], v[148:149], v[178:179], v[152:153]
	v_cvt_pk_bf16_f32 v122, v122, v123
	v_cvt_pk_bf16_f32 v123, v124, v125
	global_store_dwordx2 v[156:157], v[122:123], off
	v_cvt_pk_bf16_f32 v122, v126, v127
	v_cvt_pk_bf16_f32 v123, v162, v163
	global_store_dwordx2 v[144:145], v[122:123], off
	v_pk_mul_f32 v[122:123], v[120:121], v[158:159] op_sel_hi:[1,0]
	v_pk_mul_f32 v[124:125], v[118:119], v[158:159] op_sel_hi:[1,0]
	v_pk_mul_f32 v[146:147], v[114:115], v[158:159] op_sel_hi:[1,0]
	v_pk_mul_f32 v[148:149], v[116:117], v[158:159] op_sel_hi:[1,0]
	s_waitcnt vmcnt(6)
	v_pk_mul_f32 v[126:127], v[124:125], v[188:189]
	v_pk_mul_f32 v[128:129], v[122:123], v[190:191]
	s_waitcnt vmcnt(4)
	v_mov_b32_e32 v150, v196
	s_waitcnt vmcnt(3)
	v_pk_mul_f32 v[116:117], v[148:149], v[202:203]
	v_pk_mul_f32 v[114:115], v[146:147], v[200:201]
	v_mov_b32_e32 v146, v192
	v_mov_b32_e32 v147, v194
	v_mov_b32_e32 v151, v198
	v_mov_b32_e32 v198, v197
	v_mov_b32_e32 v194, v193
	v_pk_mul_f32 v[148:149], v[146:147], v[114:115]
	v_pk_mul_f32 v[152:153], v[150:151], v[116:117]
	v_pk_mul_f32 v[114:115], v[194:195], v[114:115]
	v_pk_mul_f32 v[116:117], v[198:199], v[116:117]
	v_pk_fma_f32 v[114:115], v[126:127], v[146:147], v[114:115] neg_lo:[0,0,1] neg_hi:[0,0,1]
	v_pk_fma_f32 v[116:117], v[128:129], v[150:151], v[116:117] neg_lo:[0,0,1] neg_hi:[0,0,1]
	v_pk_fma_f32 v[122:123], v[128:129], v[198:199], v[152:153]
	v_pk_fma_f32 v[118:119], v[126:127], v[194:195], v[148:149]
	v_cvt_pk_bf16_f32 v114, v114, v115
	v_cvt_pk_bf16_f32 v115, v116, v117
	global_store_dwordx2 v[156:157], v[114:115], off offset:8
	v_cvt_pk_bf16_f32 v114, v118, v119
	v_cvt_pk_bf16_f32 v115, v122, v123
	global_store_dwordx2 v[144:145], v[114:115], off offset:8
; template <int K> __device__ __forceinline__ float swz(float v) { return __int_as_float(__builtin_amdgcn_ds_swizzle(__float_as_int(v), (K << 10) | 0x1f)); }
; __device__ __forceinline__ float x32_sum(float v) { auto r = __builtin_amdgcn_permlane32_swap(__float_as_uint(v), __float_as_uint(v), false, false); return __uint_as_float(r[0]) + __uint_as_float(r[1]); }
; __device__ __forceinline__ unsigned cvt_pk_bf16(float lo, float hi) { const f32x2c f = {lo, hi}; return __builtin_bit_cast(unsigned, __builtin_convertvector(f, bf16x2c)); }
;     __device__ __forceinline__ void operator()(const f32x4 (&acc)[2][2][4][2], const Unit& u, int wr, int wc, int, int) const {
;     ...
;             for (int m = 0; m < 4; ++m) {
;                 const int row = rowb + ai * HALF + m * 16;
;                 float ss = 0.f;
; #pragma unroll
;                 for (int j = 0; j < 4; ++j) ss += acc[ai][0][m][0][j] * acc[ai][0][m][0][j] + acc[ai][0][m][1][j] * acc[ai][0][m][1][j] + acc[ai][1][m][0][j] * acc[ai][1][m][0][j] + acc[ai][1][m][1][j] * acc[ai][1][m][1][j];
;                 ss += ::swz<16>(ss); ss = ::x32_sum(ss);
;                 float rs = rsqrtf(ss * inv_cnt + 1e-6f) * sc; rs = is_v ? 1.0f : rs;
;                 const int pos = row & 2047, pp = rot ? ((fq & 1) ? (pos & 63) : (pos >> 6)) : 0;
;                 const float* rt = rope + pp * 16;
;                 bf16_t* dst = obase + (unsigned)(row * ostride + ocol);
; #pragma unroll
;                 for (int n = 0; n < 2; ++n) {
;                     const f32x4 g1 = *(const f32x4*)(g + 4 * n), g2 = *(const f32x4*)(g + sbj + 4 * n);
;                     const f32x4 t0 = *(const f32x4*)(rt + 8 * n), t1 = *(const f32x4*)(rt + 8 * n + 4);
;                     const f32x4 c = (f32x4){t0[0], t0[2], t1[0], t1[2]}, s = (f32x4){t0[1], t0[3], t1[1], t1[3]};
;                     const f32x4 a1 = acc[ai][0][m][n] * rs * g1, a2 = acc[ai][1][m][n] * rs * g2;
;                     const f32x4 o1 = a1 * c - a2 * s, o2 = a1 * s + a2 * c;
;                     if (st_ok) { u32x2 w; w.x = cvt_pk_bf16(o1[0], o1[1]); w.y = cvt_pk_bf16(o1[2], o1[3]); *(u32x2*)(dst + 4 * n) = w;
;                         w.x = cvt_pk_bf16(o2[0], o2[1]); w.y = cvt_pk_bf16(o2[2], o2[3]); *(u32x2*)(dst + sbj + 4 * n) = w; }
.LBB0_671:
	s_or_b64 exec, exec, s[2:3]
	v_mul_f32_e32 v114, v102, v102
	v_mul_f32_e32 v115, v103, v103
	v_fmac_f32_e32 v114, v110, v110
	v_fmac_f32_e32 v115, v111, v111
	v_fmac_f32_e32 v114, v106, v106
	v_fmac_f32_e32 v115, v107, v107
	v_fmac_f32_e32 v114, v98, v98
	v_fmac_f32_e32 v115, v99, v99
	v_add_f32_e32 v114, v114, v115
	v_mul_f32_e32 v115, v104, v104
	v_fmac_f32_e32 v115, v112, v112
	v_fmac_f32_e32 v115, v108, v108
	v_fmac_f32_e32 v115, v100, v100
	v_add_f32_e32 v114, v115, v114
	v_mul_f32_e32 v115, v105, v105
	v_fmac_f32_e32 v115, v113, v113
	v_fmac_f32_e32 v115, v109, v109
	v_fmac_f32_e32 v115, v101, v101
	v_add_f32_e32 v114, v115, v114
	ds_swizzle_b32 v115, v114 offset:swizzle(SWAP,16)
	v_or_b32_e32 v119, 16, v161
	v_mov_b32_e32 v250, s17
	v_cndmask_b32_e64 v250, v119, v250, s[40:41]
	v_lshlrev_b32_e32 v250, 4, v250
	v_cndmask_b32_e32 v250, 0, v250, vcc
	v_lshlrev_b32_e32 v251, 2, v250
	global_load_dwordx4 v[172:175], v251, s[22:23]
	global_load_dwordx4 v[176:179], v251, s[22:23] offset:16
	global_load_dwordx4 v[180:183], v[140:141], off
	global_load_dwordx4 v[184:187], v[138:139], off offset:16
	global_load_dwordx4 v[188:191], v251, s[22:23] offset:32
	global_load_dwordx4 v[192:195], v251, s[22:23] offset:48
	global_load_dwordx4 v[196:199], v[140:141], off offset:16
	s_waitcnt lgkmcnt(0)
	v_add_f32_e32 v118, v114, v115
	v_mov_b32_e32 v120, v118
	s_nop 1
	v_permlane32_swap_b32_e32 v118, v120
	s_and_saveexec_b64 s[2:3], s[20:21]
	v_or_b32_e32 v114, 16, v160
	v_add_f32_e32 v118, v118, v120
	v_mad_u64_u32 v[114:115], s[42:43], s26, v114, v[142:143]
	v_fmaak_f32 v118, v159, v118, 0x358637bd
	v_cmp_gt_f32_e64 s[42:43], s88, v118
	v_mul_f32_e32 v120, 0x4b800000, v118
	v_mov_b32_e32 v115, v0
	v_cndmask_b32_e64 v118, v118, v120, s[42:43]
	v_rsq_f32_e32 v118, v118
	v_lshl_add_u64 v[116:117], v[114:115], 1, s[60:61]
	s_lshl_b32 s54, s16, 1
	v_lshl_add_u64 v[114:115], v[116:117], 0, s[54:55]
	v_mul_f32_e32 v120, 0x45800000, v118
	v_cndmask_b32_e64 v118, v118, v120, s[42:43]
	v_mul_f32_e32 v118, v143, v118
	v_cndmask_b32_e64 v118, v118, 1.0, s[50:51]
	v_pk_mul_f32 v[120:121], v[112:113], v[118:119] op_sel_hi:[1,0]
	v_pk_mul_f32 v[122:123], v[110:111], v[118:119] op_sel_hi:[1,0]
	global_load_dwordx4 v[200:203], v[138:139], off
	v_pk_mul_f32 v[128:129], v[106:107], v[118:119] op_sel_hi:[1,0]
	v_pk_mul_f32 v[144:145], v[108:109], v[118:119] op_sel_hi:[1,0]
	s_waitcnt vmcnt(12)
	v_pk_mul_f32 v[124:125], v[122:123], v[204:205]
	v_pk_mul_f32 v[126:127], v[120:121], v[206:207]
	s_waitcnt vmcnt(6)
	v_mov_b32_e32 v146, v176
	s_waitcnt vmcnt(5)
	v_pk_mul_f32 v[108:109], v[144:145], v[182:183]
	v_pk_mul_f32 v[106:107], v[128:129], v[180:181]
	v_mov_b32_e32 v128, v172
	v_mov_b32_e32 v129, v174
	v_mov_b32_e32 v147, v178
	v_mov_b32_e32 v178, v177
	v_mov_b32_e32 v174, v173
	v_pk_mul_f32 v[144:145], v[128:129], v[106:107]
	v_pk_mul_f32 v[148:149], v[146:147], v[108:109]
	v_pk_mul_f32 v[106:107], v[174:175], v[106:107]
	v_pk_mul_f32 v[108:109], v[178:179], v[108:109]
	v_pk_fma_f32 v[106:107], v[124:125], v[128:129], v[106:107] neg_lo:[0,0,1] neg_hi:[0,0,1]
	v_pk_fma_f32 v[108:109], v[126:127], v[146:147], v[108:109] neg_lo:[0,0,1] neg_hi:[0,0,1]
	v_pk_fma_f32 v[120:121], v[126:127], v[178:179], v[148:149]
	v_pk_fma_f32 v[110:111], v[124:125], v[174:175], v[144:145]
	v_cvt_pk_bf16_f32 v106, v106, v107
	v_cvt_pk_bf16_f32 v107, v108, v109
	global_store_dwordx2 v[116:117], v[106:107], off
	v_cvt_pk_bf16_f32 v106, v110, v111
	v_cvt_pk_bf16_f32 v107, v120, v121
	global_store_dwordx2 v[114:115], v[106:107], off
	v_pk_mul_f32 v[106:107], v[104:105], v[118:119] op_sel_hi:[1,0]
	v_pk_mul_f32 v[108:109], v[102:103], v[118:119] op_sel_hi:[1,0]
	v_pk_mul_f32 v[120:121], v[98:99], v[118:119] op_sel_hi:[1,0]
	v_pk_mul_f32 v[122:123], v[100:101], v[118:119] op_sel_hi:[1,0]
	s_waitcnt vmcnt(6)
	v_pk_mul_f32 v[110:111], v[108:109], v[184:185]
	v_pk_mul_f32 v[112:113], v[106:107], v[186:187]
	s_waitcnt vmcnt(4)
	v_mov_b32_e32 v124, v192
	s_waitcnt vmcnt(3)
	v_pk_mul_f32 v[100:101], v[122:123], v[198:199]
	v_pk_mul_f32 v[98:99], v[120:121], v[196:197]
	v_mov_b32_e32 v120, v188
	v_mov_b32_e32 v121, v190
	v_mov_b32_e32 v125, v194
	v_mov_b32_e32 v194, v193
	v_mov_b32_e32 v190, v189
	v_pk_mul_f32 v[122:123], v[120:121], v[98:99]
	v_pk_mul_f32 v[126:127], v[124:125], v[100:101]
	v_pk_mul_f32 v[98:99], v[190:191], v[98:99]
	v_pk_mul_f32 v[100:101], v[194:195], v[100:101]
	v_pk_fma_f32 v[98:99], v[110:111], v[120:121], v[98:99] neg_lo:[0,0,1] neg_hi:[0,0,1]
	v_pk_fma_f32 v[100:101], v[112:113], v[124:125], v[100:101] neg_lo:[0,0,1] neg_hi:[0,0,1]
	v_pk_fma_f32 v[106:107], v[112:113], v[194:195], v[126:127]
	v_pk_fma_f32 v[102:103], v[110:111], v[190:191], v[122:123]
	v_cvt_pk_bf16_f32 v98, v98, v99
	v_cvt_pk_bf16_f32 v99, v100, v101
	global_store_dwordx2 v[116:117], v[98:99], off offset:8
	v_cvt_pk_bf16_f32 v98, v102, v103
	v_cvt_pk_bf16_f32 v99, v106, v107
	global_store_dwordx2 v[114:115], v[98:99], off offset:8
; template <int K> __device__ __forceinline__ float swz(float v) { return __int_as_float(__builtin_amdgcn_ds_swizzle(__float_as_int(v), (K << 10) | 0x1f)); }
; __device__ __forceinline__ float x32_sum(float v) { auto r = __builtin_amdgcn_permlane32_swap(__float_as_uint(v), __float_as_uint(v), false, false); return __uint_as_float(r[0]) + __uint_as_float(r[1]); }
; __device__ __forceinline__ unsigned cvt_pk_bf16(float lo, float hi) { const f32x2c f = {lo, hi}; return __builtin_bit_cast(unsigned, __builtin_convertvector(f, bf16x2c)); }
;     __device__ __forceinline__ void operator()(const f32x4 (&acc)[2][2][4][2], const Unit& u, int wr, int wc, int, int) const {
;     ...
;             for (int m = 0; m < 4; ++m) {
;                 const int row = rowb + ai * HALF + m * 16;
;                 float ss = 0.f;
; #pragma unroll
;                 for (int j = 0; j < 4; ++j) ss += acc[ai][0][m][0][j] * acc[ai][0][m][0][j] + acc[ai][0][m][1][j] * acc[ai][0][m][1][j] + acc[ai][1][m][0][j] * acc[ai][1][m][0][j] + acc[ai][1][m][1][j] * acc[ai][1][m][1][j];
;                 ss += ::swz<16>(ss); ss = ::x32_sum(ss);
;                 float rs = rsqrtf(ss * inv_cnt + 1e-6f) * sc; rs = is_v ? 1.0f : rs;
;                 const int pos = row & 2047, pp = rot ? ((fq & 1) ? (pos & 63) : (pos >> 6)) : 0;
;                 const float* rt = rope + pp * 16;
;                 bf16_t* dst = obase + (unsigned)(row * ostride + ocol);
; #pragma unroll
;                 for (int n = 0; n < 2; ++n) {
;                     const f32x4 g1 = *(const f32x4*)(g + 4 * n), g2 = *(const f32x4*)(g + sbj + 4 * n);
;                     const f32x4 t0 = *(const f32x4*)(rt + 8 * n), t1 = *(const f32x4*)(rt + 8 * n + 4);
;                     const f32x4 c = (f32x4){t0[0], t0[2], t1[0], t1[2]}, s = (f32x4){t0[1], t0[3], t1[1], t1[3]};
;                     const f32x4 a1 = acc[ai][0][m][n] * rs * g1, a2 = acc[ai][1][m][n] * rs * g2;
;                     const f32x4 o1 = a1 * c - a2 * s, o2 = a1 * s + a2 * c;
;                     if (st_ok) { u32x2 w; w.x = cvt_pk_bf16(o1[0], o1[1]); w.y = cvt_pk_bf16(o1[2], o1[3]); *(u32x2*)(dst + 4 * n) = w;
;                         w.x = cvt_pk_bf16(o2[0], o2[1]); w.y = cvt_pk_bf16(o2[2], o2[3]); *(u32x2*)(dst + sbj + 4 * n) = w; }
.LBB0_673:
	s_or_b64 exec, exec, s[2:3]
	v_mul_f32_e32 v98, v86, v86
	v_mul_f32_e32 v99, v87, v87
	v_fmac_f32_e32 v98, v94, v94
	v_fmac_f32_e32 v99, v95, v95
	v_fmac_f32_e32 v98, v90, v90
	v_fmac_f32_e32 v99, v91, v91
	v_fmac_f32_e32 v98, v82, v82
	v_fmac_f32_e32 v99, v83, v83
	v_add_f32_e32 v98, v98, v99
	v_mul_f32_e32 v99, v88, v88
	v_fmac_f32_e32 v99, v96, v96
	v_fmac_f32_e32 v99, v92, v92
	v_fmac_f32_e32 v99, v84, v84
	v_add_f32_e32 v98, v99, v98
	v_mul_f32_e32 v99, v89, v89
	v_fmac_f32_e32 v99, v97, v97
	v_fmac_f32_e32 v99, v93, v93
	v_fmac_f32_e32 v99, v85, v85
	v_add_f32_e32 v98, v99, v98
	ds_swizzle_b32 v99, v98 offset:swizzle(SWAP,16)
	v_or_b32_e32 v103, 32, v161
	v_mov_b32_e32 v248, s17
	v_cndmask_b32_e64 v248, v103, v248, s[40:41]
	v_lshlrev_b32_e32 v248, 4, v248
	v_cndmask_b32_e32 v248, 0, v248, vcc
	v_lshlrev_b32_e32 v249, 2, v248
	global_load_dwordx4 v[172:175], v249, s[22:23]
	global_load_dwordx4 v[176:179], v249, s[22:23] offset:16
	global_load_dwordx4 v[180:183], v[140:141], off
	global_load_dwordx4 v[184:187], v[138:139], off offset:16
	global_load_dwordx4 v[188:191], v249, s[22:23] offset:32
	global_load_dwordx4 v[192:195], v249, s[22:23] offset:48
	global_load_dwordx4 v[196:199], v[140:141], off offset:16
	s_waitcnt lgkmcnt(0)
	v_add_f32_e32 v102, v98, v99
	v_mov_b32_e32 v104, v102
	s_nop 1
	v_permlane32_swap_b32_e32 v102, v104
	s_and_saveexec_b64 s[2:3], s[20:21]
	v_or_b32_e32 v98, 32, v160
	v_add_f32_e32 v102, v102, v104
	v_mad_u64_u32 v[98:99], s[42:43], s26, v98, v[142:143]
	v_fmaak_f32 v102, v159, v102, 0x358637bd
	v_cmp_gt_f32_e64 s[42:43], s88, v102
	v_mul_f32_e32 v104, 0x4b800000, v102
	v_mov_b32_e32 v99, v0
	v_cndmask_b32_e64 v102, v102, v104, s[42:43]
	v_rsq_f32_e32 v102, v102
	v_lshl_add_u64 v[100:101], v[98:99], 1, s[60:61]
	s_lshl_b32 s54, s16, 1
	v_lshl_add_u64 v[98:99], v[100:101], 0, s[54:55]
	v_mul_f32_e32 v104, 0x45800000, v102
	v_cndmask_b32_e64 v102, v102, v104, s[42:43]
	v_mul_f32_e32 v102, v143, v102
	v_cndmask_b32_e64 v102, v102, 1.0, s[50:51]
	v_pk_mul_f32 v[104:105], v[96:97], v[102:103] op_sel_hi:[1,0]
	v_pk_mul_f32 v[106:107], v[94:95], v[102:103] op_sel_hi:[1,0]
	global_load_dwordx4 v[204:207], v[138:139], off
	v_pk_mul_f32 v[112:113], v[90:91], v[102:103] op_sel_hi:[1,0]
	v_pk_mul_f32 v[114:115], v[92:93], v[102:103] op_sel_hi:[1,0]
	s_waitcnt vmcnt(12)
	v_pk_mul_f32 v[108:109], v[106:107], v[200:201]
	v_pk_mul_f32 v[110:111], v[104:105], v[202:203]
	s_waitcnt vmcnt(6)
	v_mov_b32_e32 v116, v176
	s_waitcnt vmcnt(5)
	v_pk_mul_f32 v[92:93], v[114:115], v[182:183]
	v_pk_mul_f32 v[90:91], v[112:113], v[180:181]
	v_mov_b32_e32 v112, v172
	v_mov_b32_e32 v113, v174
	v_mov_b32_e32 v117, v178
	v_mov_b32_e32 v178, v177
	v_mov_b32_e32 v174, v173
	v_pk_mul_f32 v[114:115], v[112:113], v[90:91]
	v_pk_mul_f32 v[120:121], v[116:117], v[92:93]
	v_pk_mul_f32 v[90:91], v[174:175], v[90:91]
	v_pk_mul_f32 v[92:93], v[178:179], v[92:93]
	v_pk_fma_f32 v[90:91], v[108:109], v[112:113], v[90:91] neg_lo:[0,0,1] neg_hi:[0,0,1]
	v_pk_fma_f32 v[92:93], v[110:111], v[116:117], v[92:93] neg_lo:[0,0,1] neg_hi:[0,0,1]
	v_pk_fma_f32 v[104:105], v[110:111], v[178:179], v[120:121]
	v_pk_fma_f32 v[94:95], v[108:109], v[174:175], v[114:115]
	v_cvt_pk_bf16_f32 v90, v90, v91
	v_cvt_pk_bf16_f32 v91, v92, v93
	global_store_dwordx2 v[100:101], v[90:91], off
	v_cvt_pk_bf16_f32 v90, v94, v95
	v_cvt_pk_bf16_f32 v91, v104, v105
	global_store_dwordx2 v[98:99], v[90:91], off
	v_pk_mul_f32 v[90:91], v[88:89], v[102:103] op_sel_hi:[1,0]
	v_pk_mul_f32 v[92:93], v[86:87], v[102:103] op_sel_hi:[1,0]
	v_pk_mul_f32 v[104:105], v[82:83], v[102:103] op_sel_hi:[1,0]
	v_pk_mul_f32 v[106:107], v[84:85], v[102:103] op_sel_hi:[1,0]
	s_waitcnt vmcnt(6)
	v_pk_mul_f32 v[94:95], v[92:93], v[184:185]
	v_pk_mul_f32 v[96:97], v[90:91], v[186:187]
	s_waitcnt vmcnt(4)
	v_mov_b32_e32 v108, v192
	s_waitcnt vmcnt(3)
	v_pk_mul_f32 v[84:85], v[106:107], v[198:199]
	v_pk_mul_f32 v[82:83], v[104:105], v[196:197]
	v_mov_b32_e32 v104, v188
	v_mov_b32_e32 v105, v190
	v_mov_b32_e32 v109, v194
	v_mov_b32_e32 v194, v193
	v_mov_b32_e32 v190, v189
	v_pk_mul_f32 v[106:107], v[104:105], v[82:83]
	v_pk_mul_f32 v[110:111], v[108:109], v[84:85]
	v_pk_mul_f32 v[82:83], v[190:191], v[82:83]
	v_pk_mul_f32 v[84:85], v[194:195], v[84:85]
	v_pk_fma_f32 v[82:83], v[94:95], v[104:105], v[82:83] neg_lo:[0,0,1] neg_hi:[0,0,1]
	v_pk_fma_f32 v[84:85], v[96:97], v[108:109], v[84:85] neg_lo:[0,0,1] neg_hi:[0,0,1]
	v_pk_fma_f32 v[90:91], v[96:97], v[194:195], v[110:111]
	v_pk_fma_f32 v[86:87], v[94:95], v[190:191], v[106:107]
	v_cvt_pk_bf16_f32 v82, v82, v83
	v_cvt_pk_bf16_f32 v83, v84, v85
	global_store_dwordx2 v[100:101], v[82:83], off offset:8
	v_cvt_pk_bf16_f32 v82, v86, v87
	v_cvt_pk_bf16_f32 v83, v90, v91
	global_store_dwordx2 v[98:99], v[82:83], off offset:8
; template <int K> __device__ __forceinline__ float swz(float v) { return __int_as_float(__builtin_amdgcn_ds_swizzle(__float_as_int(v), (K << 10) | 0x1f)); }
; __device__ __forceinline__ float x32_sum(float v) { auto r = __builtin_amdgcn_permlane32_swap(__float_as_uint(v), __float_as_uint(v), false, false); return __uint_as_float(r[0]) + __uint_as_float(r[1]); }
; __device__ __forceinline__ unsigned cvt_pk_bf16(float lo, float hi) { const f32x2c f = {lo, hi}; return __builtin_bit_cast(unsigned, __builtin_convertvector(f, bf16x2c)); }
;     __device__ __forceinline__ void operator()(const f32x4 (&acc)[2][2][4][2], const Unit& u, int wr, int wc, int, int) const {
;     ...
;             for (int m = 0; m < 4; ++m) {
;                 const int row = rowb + ai * HALF + m * 16;
;                 float ss = 0.f;
; #pragma unroll
;                 for (int j = 0; j < 4; ++j) ss += acc[ai][0][m][0][j] * acc[ai][0][m][0][j] + acc[ai][0][m][1][j] * acc[ai][0][m][1][j] + acc[ai][1][m][0][j] * acc[ai][1][m][0][j] + acc[ai][1][m][1][j] * acc[ai][1][m][1][j];
;                 ss += ::swz<16>(ss); ss = ::x32_sum(ss);
;                 float rs = rsqrtf(ss * inv_cnt + 1e-6f) * sc; rs = is_v ? 1.0f : rs;
;                 const int pos = row & 2047, pp = rot ? ((fq & 1) ? (pos & 63) : (pos >> 6)) : 0;
;                 const float* rt = rope + pp * 16;
;                 bf16_t* dst = obase + (unsigned)(row * ostride + ocol);
; #pragma unroll
;                 for (int n = 0; n < 2; ++n) {
;                     const f32x4 g1 = *(const f32x4*)(g + 4 * n), g2 = *(const f32x4*)(g + sbj + 4 * n);
;                     const f32x4 t0 = *(const f32x4*)(rt + 8 * n), t1 = *(const f32x4*)(rt + 8 * n + 4);
;                     const f32x4 c = (f32x4){t0[0], t0[2], t1[0], t1[2]}, s = (f32x4){t0[1], t0[3], t1[1], t1[3]};
;                     const f32x4 a1 = acc[ai][0][m][n] * rs * g1, a2 = acc[ai][1][m][n] * rs * g2;
;                     const f32x4 o1 = a1 * c - a2 * s, o2 = a1 * s + a2 * c;
;                     if (st_ok) { u32x2 w; w.x = cvt_pk_bf16(o1[0], o1[1]); w.y = cvt_pk_bf16(o1[2], o1[3]); *(u32x2*)(dst + 4 * n) = w;
;                         w.x = cvt_pk_bf16(o2[0], o2[1]); w.y = cvt_pk_bf16(o2[2], o2[3]); *(u32x2*)(dst + sbj + 4 * n) = w; }
.LBB0_675:
	s_or_b64 exec, exec, s[2:3]
	v_mul_f32_e32 v82, v70, v70
	v_mul_f32_e32 v83, v71, v71
	v_fmac_f32_e32 v82, v78, v78
	v_fmac_f32_e32 v83, v79, v79
	v_fmac_f32_e32 v82, v74, v74
	v_fmac_f32_e32 v83, v75, v75
	v_fmac_f32_e32 v82, v66, v66
	v_fmac_f32_e32 v83, v67, v67
	v_add_f32_e32 v82, v82, v83
	v_mul_f32_e32 v83, v72, v72
	v_fmac_f32_e32 v83, v80, v80
	v_fmac_f32_e32 v83, v76, v76
	v_fmac_f32_e32 v83, v68, v68
	v_add_f32_e32 v82, v83, v82
	v_mul_f32_e32 v83, v73, v73
	v_fmac_f32_e32 v83, v81, v81
	v_fmac_f32_e32 v83, v77, v77
	v_fmac_f32_e32 v83, v69, v69
	v_add_f32_e32 v82, v83, v82
	ds_swizzle_b32 v83, v82 offset:swizzle(SWAP,16)
	v_or_b32_e32 v87, 48, v161
	v_mov_b32_e32 v250, s17
	v_cndmask_b32_e64 v250, v87, v250, s[40:41]
	v_lshlrev_b32_e32 v250, 4, v250
	v_cndmask_b32_e32 v250, 0, v250, vcc
	v_lshlrev_b32_e32 v251, 2, v250
	global_load_dwordx4 v[172:175], v251, s[22:23]
	global_load_dwordx4 v[176:179], v251, s[22:23] offset:16
	global_load_dwordx4 v[180:183], v[140:141], off
	global_load_dwordx4 v[184:187], v[138:139], off offset:16
	global_load_dwordx4 v[188:191], v251, s[22:23] offset:32
	global_load_dwordx4 v[192:195], v251, s[22:23] offset:48
	global_load_dwordx4 v[196:199], v[140:141], off offset:16
	s_waitcnt lgkmcnt(0)
	v_add_f32_e32 v86, v82, v83
	v_mov_b32_e32 v88, v86
	s_nop 1
	v_permlane32_swap_b32_e32 v86, v88
	s_and_saveexec_b64 s[2:3], s[20:21]
	v_or_b32_e32 v82, 48, v160
	v_add_f32_e32 v86, v86, v88
	v_mad_u64_u32 v[82:83], s[42:43], s26, v82, v[142:143]
	v_fmaak_f32 v86, v159, v86, 0x358637bd
	v_cmp_gt_f32_e64 s[42:43], s88, v86
	v_mul_f32_e32 v88, 0x4b800000, v86
	v_mov_b32_e32 v83, v0
	v_cndmask_b32_e64 v86, v86, v88, s[42:43]
	v_rsq_f32_e32 v86, v86
	v_lshl_add_u64 v[84:85], v[82:83], 1, s[60:61]
	s_lshl_b32 s54, s16, 1
	v_lshl_add_u64 v[82:83], v[84:85], 0, s[54:55]
	v_mul_f32_e32 v88, 0x45800000, v86
	v_cndmask_b32_e64 v86, v86, v88, s[42:43]
	v_mul_f32_e32 v86, v143, v86
	v_cndmask_b32_e64 v86, v86, 1.0, s[50:51]
	v_pk_mul_f32 v[88:89], v[80:81], v[86:87] op_sel_hi:[1,0]
	v_pk_mul_f32 v[90:91], v[78:79], v[86:87] op_sel_hi:[1,0]
	global_load_dwordx4 v[200:203], v[138:139], off
	v_pk_mul_f32 v[96:97], v[74:75], v[86:87] op_sel_hi:[1,0]
	v_pk_mul_f32 v[98:99], v[76:77], v[86:87] op_sel_hi:[1,0]
	s_waitcnt vmcnt(12)
	v_pk_mul_f32 v[92:93], v[90:91], v[204:205]
	v_pk_mul_f32 v[94:95], v[88:89], v[206:207]
	s_waitcnt vmcnt(6)
	v_mov_b32_e32 v100, v176
	s_waitcnt vmcnt(5)
	v_pk_mul_f32 v[76:77], v[98:99], v[182:183]
	v_pk_mul_f32 v[74:75], v[96:97], v[180:181]
	v_mov_b32_e32 v96, v172
	v_mov_b32_e32 v97, v174
	v_mov_b32_e32 v101, v178
	v_mov_b32_e32 v178, v177
	v_mov_b32_e32 v174, v173
	v_pk_mul_f32 v[98:99], v[96:97], v[74:75]
	v_pk_mul_f32 v[104:105], v[100:101], v[76:77]
	v_pk_mul_f32 v[74:75], v[174:175], v[74:75]
	v_pk_mul_f32 v[76:77], v[178:179], v[76:77]
	v_pk_fma_f32 v[74:75], v[92:93], v[96:97], v[74:75] neg_lo:[0,0,1] neg_hi:[0,0,1]
	v_pk_fma_f32 v[76:77], v[94:95], v[100:101], v[76:77] neg_lo:[0,0,1] neg_hi:[0,0,1]
	v_pk_fma_f32 v[88:89], v[94:95], v[178:179], v[104:105]
	v_pk_fma_f32 v[78:79], v[92:93], v[174:175], v[98:99]
	v_cvt_pk_bf16_f32 v74, v74, v75
	v_cvt_pk_bf16_f32 v75, v76, v77
	global_store_dwordx2 v[84:85], v[74:75], off
	v_cvt_pk_bf16_f32 v74, v78, v79
	v_cvt_pk_bf16_f32 v75, v88, v89
	global_store_dwordx2 v[82:83], v[74:75], off
	v_pk_mul_f32 v[74:75], v[72:73], v[86:87] op_sel_hi:[1,0]
	v_pk_mul_f32 v[76:77], v[70:71], v[86:87] op_sel_hi:[1,0]
	v_pk_mul_f32 v[88:89], v[66:67], v[86:87] op_sel_hi:[1,0]
	v_pk_mul_f32 v[90:91], v[68:69], v[86:87] op_sel_hi:[1,0]
	s_waitcnt vmcnt(6)
	v_pk_mul_f32 v[78:79], v[76:77], v[184:185]
	v_pk_mul_f32 v[80:81], v[74:75], v[186:187]
	s_waitcnt vmcnt(4)
	v_mov_b32_e32 v92, v192
	s_waitcnt vmcnt(3)
	v_pk_mul_f32 v[68:69], v[90:91], v[198:199]
	v_pk_mul_f32 v[66:67], v[88:89], v[196:197]
	v_mov_b32_e32 v88, v188
	v_mov_b32_e32 v89, v190
	v_mov_b32_e32 v93, v194
	v_mov_b32_e32 v194, v193
	v_mov_b32_e32 v190, v189
	v_pk_mul_f32 v[90:91], v[88:89], v[66:67]
	v_pk_mul_f32 v[94:95], v[92:93], v[68:69]
	v_pk_mul_f32 v[66:67], v[190:191], v[66:67]
	v_pk_mul_f32 v[68:69], v[194:195], v[68:69]
	v_pk_fma_f32 v[66:67], v[78:79], v[88:89], v[66:67] neg_lo:[0,0,1] neg_hi:[0,0,1]
	v_pk_fma_f32 v[68:69], v[80:81], v[92:93], v[68:69] neg_lo:[0,0,1] neg_hi:[0,0,1]
	v_pk_fma_f32 v[74:75], v[80:81], v[194:195], v[94:95]
	v_pk_fma_f32 v[70:71], v[78:79], v[190:191], v[90:91]
	v_cvt_pk_bf16_f32 v66, v66, v67
	v_cvt_pk_bf16_f32 v67, v68, v69
	global_store_dwordx2 v[84:85], v[66:67], off offset:8
	v_cvt_pk_bf16_f32 v66, v70, v71
	v_cvt_pk_bf16_f32 v67, v74, v75
	global_store_dwordx2 v[82:83], v[66:67], off offset:8
; template <int K> __device__ __forceinline__ float swz(float v) { return __int_as_float(__builtin_amdgcn_ds_swizzle(__float_as_int(v), (K << 10) | 0x1f)); }
; __device__ __forceinline__ float x32_sum(float v) { auto r = __builtin_amdgcn_permlane32_swap(__float_as_uint(v), __float_as_uint(v), false, false); return __uint_as_float(r[0]) + __uint_as_float(r[1]); }
; __device__ __forceinline__ unsigned cvt_pk_bf16(float lo, float hi) { const f32x2c f = {lo, hi}; return __builtin_bit_cast(unsigned, __builtin_convertvector(f, bf16x2c)); }
;     __device__ __forceinline__ void operator()(const f32x4 (&acc)[2][2][4][2], const Unit& u, int wr, int wc, int, int) const {
;     ...
;             for (int m = 0; m < 4; ++m) {
;                 const int row = rowb + ai * HALF + m * 16;
;                 float ss = 0.f;
; #pragma unroll
;                 for (int j = 0; j < 4; ++j) ss += acc[ai][0][m][0][j] * acc[ai][0][m][0][j] + acc[ai][0][m][1][j] * acc[ai][0][m][1][j] + acc[ai][1][m][0][j] * acc[ai][1][m][0][j] + acc[ai][1][m][1][j] * acc[ai][1][m][1][j];
;                 ss += ::swz<16>(ss); ss = ::x32_sum(ss);
;                 float rs = rsqrtf(ss * inv_cnt + 1e-6f) * sc; rs = is_v ? 1.0f : rs;
;                 const int pos = row & 2047, pp = rot ? ((fq & 1) ? (pos & 63) : (pos >> 6)) : 0;
;                 const float* rt = rope + pp * 16;
;                 bf16_t* dst = obase + (unsigned)(row * ostride + ocol);
; #pragma unroll
;                 for (int n = 0; n < 2; ++n) {
;                     const f32x4 g1 = *(const f32x4*)(g + 4 * n), g2 = *(const f32x4*)(g + sbj + 4 * n);
;                     const f32x4 t0 = *(const f32x4*)(rt + 8 * n), t1 = *(const f32x4*)(rt + 8 * n + 4);
;                     const f32x4 c = (f32x4){t0[0], t0[2], t1[0], t1[2]}, s = (f32x4){t0[1], t0[3], t1[1], t1[3]};
;                     const f32x4 a1 = acc[ai][0][m][n] * rs * g1, a2 = acc[ai][1][m][n] * rs * g2;
;                     const f32x4 o1 = a1 * c - a2 * s, o2 = a1 * s + a2 * c;
;                     if (st_ok) { u32x2 w; w.x = cvt_pk_bf16(o1[0], o1[1]); w.y = cvt_pk_bf16(o1[2], o1[3]); *(u32x2*)(dst + 4 * n) = w;
;                         w.x = cvt_pk_bf16(o2[0], o2[1]); w.y = cvt_pk_bf16(o2[2], o2[3]); *(u32x2*)(dst + sbj + 4 * n) = w; }
.LBB0_677:
	s_or_b64 exec, exec, s[2:3]
	v_mul_f32_e32 v66, v54, v54
	v_mul_f32_e32 v67, v55, v55
	v_fmac_f32_e32 v66, v62, v62
	v_fmac_f32_e32 v67, v63, v63
	v_fmac_f32_e32 v66, v58, v58
	v_fmac_f32_e32 v67, v59, v59
	v_fmac_f32_e32 v66, v50, v50
	v_fmac_f32_e32 v67, v51, v51
	v_add_f32_e32 v66, v66, v67
	v_mul_f32_e32 v67, v56, v56
	v_fmac_f32_e32 v67, v64, v64
	v_fmac_f32_e32 v67, v60, v60
	v_fmac_f32_e32 v67, v52, v52
	v_add_f32_e32 v66, v67, v66
	v_mul_f32_e32 v67, v57, v57
	v_fmac_f32_e32 v67, v65, v65
	v_fmac_f32_e32 v67, v61, v61
	v_fmac_f32_e32 v67, v53, v53
	v_add_f32_e32 v67, v67, v66
	ds_swizzle_b32 v68, v67 offset:swizzle(SWAP,16)
	v_add_u32_e32 v66, 0x80, v160
	v_bfe_u32 v71, v66, 6, 5
	v_cndmask_b32_e64 v248, v161, v71, s[40:41]
	v_lshlrev_b32_e32 v248, 4, v248
	v_cndmask_b32_e32 v248, 0, v248, vcc
	v_lshlrev_b32_e32 v249, 2, v248
	global_load_dwordx4 v[172:175], v249, s[22:23]
	global_load_dwordx4 v[176:179], v249, s[22:23] offset:16
	global_load_dwordx4 v[180:183], v[140:141], off
	global_load_dwordx4 v[184:187], v[138:139], off offset:16
	global_load_dwordx4 v[188:191], v249, s[22:23] offset:32
	global_load_dwordx4 v[192:195], v249, s[22:23] offset:48
	global_load_dwordx4 v[196:199], v[140:141], off offset:16
	s_waitcnt lgkmcnt(0)
	v_add_f32_e32 v70, v67, v68
	v_mov_b32_e32 v72, v70
	s_nop 1
	v_permlane32_swap_b32_e32 v70, v72
	s_and_saveexec_b64 s[2:3], s[20:21]
	v_add_f32_e32 v70, v70, v72
	v_mad_u64_u32 v[66:67], s[42:43], s26, v66, v[142:143]
	v_fmaak_f32 v70, v159, v70, 0x358637bd
	v_cmp_gt_f32_e64 s[42:43], s88, v70
	v_mul_f32_e32 v72, 0x4b800000, v70
	v_mov_b32_e32 v67, v0
	v_cndmask_b32_e64 v70, v70, v72, s[42:43]
	v_rsq_f32_e32 v70, v70
	v_lshl_add_u64 v[68:69], v[66:67], 1, s[60:61]
	s_lshl_b32 s54, s16, 1
	v_lshl_add_u64 v[66:67], v[68:69], 0, s[54:55]
	v_mul_f32_e32 v72, 0x45800000, v70
	v_cndmask_b32_e64 v70, v70, v72, s[42:43]
	v_mul_f32_e32 v70, v143, v70
	v_cndmask_b32_e64 v70, v70, 1.0, s[50:51]
	v_pk_mul_f32 v[72:73], v[64:65], v[70:71] op_sel_hi:[1,0]
	v_pk_mul_f32 v[74:75], v[62:63], v[70:71] op_sel_hi:[1,0]
	global_load_dwordx4 v[204:207], v[138:139], off
	v_pk_mul_f32 v[80:81], v[58:59], v[70:71] op_sel_hi:[1,0]
	v_pk_mul_f32 v[82:83], v[60:61], v[70:71] op_sel_hi:[1,0]
	s_waitcnt vmcnt(12)
	v_pk_mul_f32 v[76:77], v[74:75], v[200:201]
	v_pk_mul_f32 v[78:79], v[72:73], v[202:203]
	v_cndmask_b32_e64 v251, v119, v71, s[40:41]
	v_lshlrev_b32_e32 v251, 4, v251
	v_cndmask_b32_e32 v251, 0, v251, vcc
	v_lshlrev_b32_e32 v251, 2, v251
	global_load_dwordx4 v[200:203], v251, s[22:23]
	global_load_dwordx4 v[212:215], v251, s[22:23] offset:16
	global_load_dwordx4 v[224:227], v[140:141], off
	s_waitcnt vmcnt(9)
	v_mov_b32_e32 v84, v176
	s_waitcnt vmcnt(8)
	v_pk_mul_f32 v[60:61], v[82:83], v[182:183]
	v_pk_mul_f32 v[58:59], v[80:81], v[180:181]
	v_mov_b32_e32 v80, v172
	v_mov_b32_e32 v81, v174
	v_mov_b32_e32 v85, v178
	v_mov_b32_e32 v178, v177
	v_mov_b32_e32 v174, v173
	v_pk_mul_f32 v[82:83], v[80:81], v[58:59]
	v_pk_mul_f32 v[88:89], v[84:85], v[60:61]
	v_pk_mul_f32 v[58:59], v[174:175], v[58:59]
	v_pk_mul_f32 v[60:61], v[178:179], v[60:61]
	v_pk_fma_f32 v[58:59], v[76:77], v[80:81], v[58:59] neg_lo:[0,0,1] neg_hi:[0,0,1]
	v_pk_fma_f32 v[60:61], v[78:79], v[84:85], v[60:61] neg_lo:[0,0,1] neg_hi:[0,0,1]
	v_pk_fma_f32 v[72:73], v[78:79], v[178:179], v[88:89]
	v_pk_fma_f32 v[62:63], v[76:77], v[174:175], v[82:83]
	v_cvt_pk_bf16_f32 v58, v58, v59
	v_cvt_pk_bf16_f32 v59, v60, v61
	global_store_dwordx2 v[68:69], v[58:59], off
	v_cvt_pk_bf16_f32 v58, v62, v63
	v_cvt_pk_bf16_f32 v59, v72, v73
	global_store_dwordx2 v[66:67], v[58:59], off
	v_pk_mul_f32 v[58:59], v[56:57], v[70:71] op_sel_hi:[1,0]
	v_pk_mul_f32 v[60:61], v[54:55], v[70:71] op_sel_hi:[1,0]
	global_load_dwordx4 v[172:175], v[138:139], off offset:16
	v_pk_mul_f32 v[72:73], v[50:51], v[70:71] op_sel_hi:[1,0]
	v_pk_mul_f32 v[74:75], v[52:53], v[70:71] op_sel_hi:[1,0]
	s_waitcnt vmcnt(10)
	v_pk_mul_f32 v[62:63], v[60:61], v[184:185]
	v_pk_mul_f32 v[64:65], v[58:59], v[186:187]
	global_load_dwordx4 v[176:179], v251, s[22:23] offset:32
	global_load_dwordx4 v[180:183], v251, s[22:23] offset:48
	global_load_dwordx4 v[184:187], v[140:141], off offset:16
	s_waitcnt vmcnt(11)
	v_mov_b32_e32 v76, v192
	s_waitcnt vmcnt(10)
	v_pk_mul_f32 v[52:53], v[74:75], v[198:199]
	v_pk_mul_f32 v[50:51], v[72:73], v[196:197]
	v_mov_b32_e32 v72, v188
	v_mov_b32_e32 v73, v190
	v_mov_b32_e32 v77, v194
	v_mov_b32_e32 v194, v193
	v_mov_b32_e32 v190, v189
	v_pk_mul_f32 v[74:75], v[72:73], v[50:51]
	v_pk_mul_f32 v[78:79], v[76:77], v[52:53]
	v_pk_mul_f32 v[50:51], v[190:191], v[50:51]
	v_pk_mul_f32 v[52:53], v[194:195], v[52:53]
	v_pk_fma_f32 v[50:51], v[62:63], v[72:73], v[50:51] neg_lo:[0,0,1] neg_hi:[0,0,1]
	v_pk_fma_f32 v[52:53], v[64:65], v[76:77], v[52:53] neg_lo:[0,0,1] neg_hi:[0,0,1]
	v_pk_fma_f32 v[58:59], v[64:65], v[194:195], v[78:79]
	v_pk_fma_f32 v[54:55], v[62:63], v[190:191], v[74:75]
	v_cvt_pk_bf16_f32 v50, v50, v51
	v_cvt_pk_bf16_f32 v51, v52, v53
	global_store_dwordx2 v[68:69], v[50:51], off offset:8
	v_cvt_pk_bf16_f32 v50, v54, v55
	v_cvt_pk_bf16_f32 v51, v58, v59
	global_store_dwordx2 v[66:67], v[50:51], off offset:8
; template <int K> __device__ __forceinline__ float swz(float v) { return __int_as_float(__builtin_amdgcn_ds_swizzle(__float_as_int(v), (K << 10) | 0x1f)); }
; __device__ __forceinline__ float x32_sum(float v) { auto r = __builtin_amdgcn_permlane32_swap(__float_as_uint(v), __float_as_uint(v), false, false); return __uint_as_float(r[0]) + __uint_as_float(r[1]); }
; __device__ __forceinline__ unsigned cvt_pk_bf16(float lo, float hi) { const f32x2c f = {lo, hi}; return __builtin_bit_cast(unsigned, __builtin_convertvector(f, bf16x2c)); }
;     __device__ __forceinline__ void operator()(const f32x4 (&acc)[2][2][4][2], const Unit& u, int wr, int wc, int, int) const {
;     ...
;             for (int m = 0; m < 4; ++m) {
;                 const int row = rowb + ai * HALF + m * 16;
;                 float ss = 0.f;
; #pragma unroll
;                 for (int j = 0; j < 4; ++j) ss += acc[ai][0][m][0][j] * acc[ai][0][m][0][j] + acc[ai][0][m][1][j] * acc[ai][0][m][1][j] + acc[ai][1][m][0][j] * acc[ai][1][m][0][j] + acc[ai][1][m][1][j] * acc[ai][1][m][1][j];
;                 ss += ::swz<16>(ss); ss = ::x32_sum(ss);
;                 float rs = rsqrtf(ss * inv_cnt + 1e-6f) * sc; rs = is_v ? 1.0f : rs;
;                 const int pos = row & 2047, pp = rot ? ((fq & 1) ? (pos & 63) : (pos >> 6)) : 0;
;                 const float* rt = rope + pp * 16;
;                 bf16_t* dst = obase + (unsigned)(row * ostride + ocol);
; #pragma unroll
;                 for (int n = 0; n < 2; ++n) {
;                     const f32x4 g1 = *(const f32x4*)(g + 4 * n), g2 = *(const f32x4*)(g + sbj + 4 * n);
;                     const f32x4 t0 = *(const f32x4*)(rt + 8 * n), t1 = *(const f32x4*)(rt + 8 * n + 4);
;                     const f32x4 c = (f32x4){t0[0], t0[2], t1[0], t1[2]}, s = (f32x4){t0[1], t0[3], t1[1], t1[3]};
;                     const f32x4 a1 = acc[ai][0][m][n] * rs * g1, a2 = acc[ai][1][m][n] * rs * g2;
;                     const f32x4 o1 = a1 * c - a2 * s, o2 = a1 * s + a2 * c;
;                     if (st_ok) { u32x2 w; w.x = cvt_pk_bf16(o1[0], o1[1]); w.y = cvt_pk_bf16(o1[2], o1[3]); *(u32x2*)(dst + 4 * n) = w;
;                         w.x = cvt_pk_bf16(o2[0], o2[1]); w.y = cvt_pk_bf16(o2[2], o2[3]); *(u32x2*)(dst + sbj + 4 * n) = w; }
.LBB0_679:
	s_or_b64 exec, exec, s[2:3]
	v_mul_f32_e32 v50, v38, v38
	v_mul_f32_e32 v51, v39, v39
	v_fmac_f32_e32 v50, v46, v46
	v_fmac_f32_e32 v51, v47, v47
	v_fmac_f32_e32 v50, v42, v42
	v_fmac_f32_e32 v51, v43, v43
	v_fmac_f32_e32 v50, v34, v34
	v_fmac_f32_e32 v51, v35, v35
	v_add_f32_e32 v50, v50, v51
	v_mul_f32_e32 v51, v40, v40
	v_fmac_f32_e32 v51, v48, v48
	v_fmac_f32_e32 v51, v44, v44
	v_fmac_f32_e32 v51, v36, v36
	v_add_f32_e32 v50, v51, v50
	v_mul_f32_e32 v51, v41, v41
	v_fmac_f32_e32 v51, v49, v49
	v_fmac_f32_e32 v51, v45, v45
	v_fmac_f32_e32 v51, v37, v37
	v_add_f32_e32 v50, v51, v50
	ds_swizzle_b32 v51, v50 offset:swizzle(SWAP,16)
	s_waitcnt lgkmcnt(0)
	v_add_f32_e32 v54, v50, v51
	v_mov_b32_e32 v55, v54
	s_nop 1
	v_permlane32_swap_b32_e32 v54, v55
	s_and_saveexec_b64 s[2:3], s[20:21]
	v_add_u32_e32 v50, 0x90, v160
	v_add_f32_e32 v54, v54, v55
	v_mad_u64_u32 v[50:51], s[42:43], s26, v50, v[142:143]
	v_fmaak_f32 v54, v159, v54, 0x358637bd
	v_cmp_gt_f32_e64 s[42:43], s88, v54
	v_mul_f32_e32 v55, 0x4b800000, v54
	v_mov_b32_e32 v51, v0
	v_cndmask_b32_e64 v54, v54, v55, s[42:43]
	v_rsq_f32_e32 v54, v54
	v_lshl_add_u64 v[52:53], v[50:51], 1, s[60:61]
	s_lshl_b32 s54, s16, 1
	v_lshl_add_u64 v[50:51], v[52:53], 0, s[54:55]
	v_mul_f32_e32 v55, 0x45800000, v54
	v_cndmask_b32_e64 v54, v54, v55, s[42:43]
	v_mul_f32_e32 v54, v143, v54
	v_cndmask_b32_e64 v54, v54, 1.0, s[50:51]
	v_pk_mul_f32 v[56:57], v[48:49], v[54:55] op_sel_hi:[1,0]
	v_pk_mul_f32 v[58:59], v[46:47], v[54:55] op_sel_hi:[1,0]
	global_load_dwordx4 v[188:191], v[138:139], off
	v_pk_mul_f32 v[64:65], v[42:43], v[54:55] op_sel_hi:[1,0]
	v_pk_mul_f32 v[66:67], v[44:45], v[54:55] op_sel_hi:[1,0]
	s_waitcnt vmcnt(12)
	v_pk_mul_f32 v[60:61], v[58:59], v[204:205]
	v_pk_mul_f32 v[62:63], v[56:57], v[206:207]
	v_cndmask_b32_e64 v249, v103, v71, s[40:41]
	v_lshlrev_b32_e32 v249, 4, v249
	v_cndmask_b32_e32 v249, 0, v249, vcc
	v_lshlrev_b32_e32 v249, 2, v249
	global_load_dwordx4 v[192:195], v249, s[22:23]
	global_load_dwordx4 v[196:199], v249, s[22:23] offset:16
	global_load_dwordx4 v[204:207], v[140:141], off
	s_waitcnt vmcnt(13)
	v_mov_b32_e32 v68, v212
	s_waitcnt vmcnt(12)
	v_pk_mul_f32 v[44:45], v[66:67], v[226:227]
	v_pk_mul_f32 v[42:43], v[64:65], v[224:225]
	v_mov_b32_e32 v64, v200
	v_mov_b32_e32 v65, v202
	v_mov_b32_e32 v69, v214
	v_mov_b32_e32 v214, v213
	v_mov_b32_e32 v202, v201
	v_pk_mul_f32 v[66:67], v[64:65], v[42:43]
	v_pk_mul_f32 v[72:73], v[68:69], v[44:45]
	v_pk_mul_f32 v[42:43], v[202:203], v[42:43]
	v_pk_mul_f32 v[44:45], v[214:215], v[44:45]
	v_pk_fma_f32 v[42:43], v[60:61], v[64:65], v[42:43] neg_lo:[0,0,1] neg_hi:[0,0,1]
	v_pk_fma_f32 v[44:45], v[62:63], v[68:69], v[44:45] neg_lo:[0,0,1] neg_hi:[0,0,1]
	v_pk_fma_f32 v[56:57], v[62:63], v[214:215], v[72:73]
	v_pk_fma_f32 v[46:47], v[60:61], v[202:203], v[66:67]
	v_cvt_pk_bf16_f32 v42, v42, v43
	v_cvt_pk_bf16_f32 v43, v44, v45
	global_store_dwordx2 v[52:53], v[42:43], off
	v_cvt_pk_bf16_f32 v42, v46, v47
	v_cvt_pk_bf16_f32 v43, v56, v57
	global_store_dwordx2 v[50:51], v[42:43], off
	v_pk_mul_f32 v[42:43], v[40:41], v[54:55] op_sel_hi:[1,0]
	v_pk_mul_f32 v[44:45], v[38:39], v[54:55] op_sel_hi:[1,0]
	global_load_dwordx4 v[200:203], v[138:139], off offset:16
	v_pk_mul_f32 v[56:57], v[34:35], v[54:55] op_sel_hi:[1,0]
	s_waitcnt vmcnt(12)
	v_pk_mul_f32 v[46:47], v[44:45], v[172:173]
	v_pk_mul_f32 v[48:49], v[42:43], v[174:175]
	global_load_dwordx4 v[172:175], v249, s[22:23] offset:32
	global_load_dwordx4 v[212:215], v249, s[22:23] offset:48
	v_pk_mul_f32 v[54:55], v[36:37], v[54:55] op_sel_hi:[1,0]
	global_load_dwordx4 v[224:227], v[140:141], off offset:16
	s_waitcnt vmcnt(13)
	v_mov_b32_e32 v58, v180
	v_mov_b32_e32 v59, v182
	s_waitcnt vmcnt(12)
	v_pk_mul_f32 v[36:37], v[54:55], v[186:187]
	v_pk_mul_f32 v[34:35], v[56:57], v[184:185]
	v_mov_b32_e32 v54, v176
	v_mov_b32_e32 v55, v178
	v_mov_b32_e32 v182, v181
	v_mov_b32_e32 v178, v177
	v_pk_mul_f32 v[56:57], v[54:55], v[34:35]
	v_pk_mul_f32 v[60:61], v[58:59], v[36:37]
	v_pk_mul_f32 v[34:35], v[178:179], v[34:35]
	v_pk_mul_f32 v[36:37], v[182:183], v[36:37]
	v_pk_fma_f32 v[34:35], v[46:47], v[54:55], v[34:35] neg_lo:[0,0,1] neg_hi:[0,0,1]
	v_pk_fma_f32 v[36:37], v[48:49], v[58:59], v[36:37] neg_lo:[0,0,1] neg_hi:[0,0,1]
	v_pk_fma_f32 v[42:43], v[48:49], v[182:183], v[60:61]
	v_pk_fma_f32 v[38:39], v[46:47], v[178:179], v[56:57]
	v_cvt_pk_bf16_f32 v34, v34, v35
	v_cvt_pk_bf16_f32 v35, v36, v37
	global_store_dwordx2 v[52:53], v[34:35], off offset:8
	v_cvt_pk_bf16_f32 v34, v38, v39
	v_cvt_pk_bf16_f32 v35, v42, v43
	global_store_dwordx2 v[50:51], v[34:35], off offset:8
; template <int K> __device__ __forceinline__ float swz(float v) { return __int_as_float(__builtin_amdgcn_ds_swizzle(__float_as_int(v), (K << 10) | 0x1f)); }
; __device__ __forceinline__ float x32_sum(float v) { auto r = __builtin_amdgcn_permlane32_swap(__float_as_uint(v), __float_as_uint(v), false, false); return __uint_as_float(r[0]) + __uint_as_float(r[1]); }
; __device__ __forceinline__ unsigned cvt_pk_bf16(float lo, float hi) { const f32x2c f = {lo, hi}; return __builtin_bit_cast(unsigned, __builtin_convertvector(f, bf16x2c)); }
;     __device__ __forceinline__ void operator()(const f32x4 (&acc)[2][2][4][2], const Unit& u, int wr, int wc, int, int) const {
;     ...
;             for (int m = 0; m < 4; ++m) {
;                 const int row = rowb + ai * HALF + m * 16;
;                 float ss = 0.f;
; #pragma unroll
;                 for (int j = 0; j < 4; ++j) ss += acc[ai][0][m][0][j] * acc[ai][0][m][0][j] + acc[ai][0][m][1][j] * acc[ai][0][m][1][j] + acc[ai][1][m][0][j] * acc[ai][1][m][0][j] + acc[ai][1][m][1][j] * acc[ai][1][m][1][j];
;                 ss += ::swz<16>(ss); ss = ::x32_sum(ss);
;                 float rs = rsqrtf(ss * inv_cnt + 1e-6f) * sc; rs = is_v ? 1.0f : rs;
;                 const int pos = row & 2047, pp = rot ? ((fq & 1) ? (pos & 63) : (pos >> 6)) : 0;
;                 const float* rt = rope + pp * 16;
;                 bf16_t* dst = obase + (unsigned)(row * ostride + ocol);
; #pragma unroll
;                 for (int n = 0; n < 2; ++n) {
;                     const f32x4 g1 = *(const f32x4*)(g + 4 * n), g2 = *(const f32x4*)(g + sbj + 4 * n);
;                     const f32x4 t0 = *(const f32x4*)(rt + 8 * n), t1 = *(const f32x4*)(rt + 8 * n + 4);
;                     const f32x4 c = (f32x4){t0[0], t0[2], t1[0], t1[2]}, s = (f32x4){t0[1], t0[3], t1[1], t1[3]};
;                     const f32x4 a1 = acc[ai][0][m][n] * rs * g1, a2 = acc[ai][1][m][n] * rs * g2;
;                     const f32x4 o1 = a1 * c - a2 * s, o2 = a1 * s + a2 * c;
;                     if (st_ok) { u32x2 w; w.x = cvt_pk_bf16(o1[0], o1[1]); w.y = cvt_pk_bf16(o1[2], o1[3]); *(u32x2*)(dst + 4 * n) = w;
;                         w.x = cvt_pk_bf16(o2[0], o2[1]); w.y = cvt_pk_bf16(o2[2], o2[3]); *(u32x2*)(dst + sbj + 4 * n) = w; }
;                 }
.LBB0_681:
	s_or_b64 exec, exec, s[2:3]
	v_mul_f32_e32 v34, v22, v22
	v_mul_f32_e32 v35, v23, v23
	v_fmac_f32_e32 v34, v30, v30
	v_fmac_f32_e32 v35, v31, v31
	v_fmac_f32_e32 v34, v26, v26
	v_fmac_f32_e32 v35, v27, v27
	v_fmac_f32_e32 v34, v18, v18
	v_fmac_f32_e32 v35, v19, v19
	v_add_f32_e32 v34, v34, v35
	v_mul_f32_e32 v35, v24, v24
	v_fmac_f32_e32 v35, v32, v32
	v_fmac_f32_e32 v35, v28, v28
	v_fmac_f32_e32 v35, v20, v20
	v_add_f32_e32 v34, v35, v34
	v_mul_f32_e32 v35, v25, v25
	v_fmac_f32_e32 v35, v33, v33
	v_fmac_f32_e32 v35, v29, v29
	v_fmac_f32_e32 v35, v21, v21
	v_add_f32_e32 v34, v35, v34
	ds_swizzle_b32 v35, v34 offset:swizzle(SWAP,16)
	s_waitcnt lgkmcnt(0)
	v_add_f32_e32 v38, v34, v35
	v_mov_b32_e32 v39, v38
	s_nop 1
	v_permlane32_swap_b32_e32 v38, v39
	s_and_saveexec_b64 s[2:3], s[20:21]
	v_add_u32_e32 v34, 0xa0, v160
	v_add_f32_e32 v38, v38, v39
	v_mad_u64_u32 v[34:35], s[42:43], s26, v34, v[142:143]
	v_fmaak_f32 v38, v159, v38, 0x358637bd
	v_cmp_gt_f32_e64 s[42:43], s88, v38
	v_mul_f32_e32 v39, 0x4b800000, v38
	v_mov_b32_e32 v35, v0
	v_cndmask_b32_e64 v38, v38, v39, s[42:43]
	v_rsq_f32_e32 v38, v38
	v_lshl_add_u64 v[36:37], v[34:35], 1, s[60:61]
	s_lshl_b32 s54, s16, 1
	v_lshl_add_u64 v[34:35], v[36:37], 0, s[54:55]
	v_mul_f32_e32 v39, 0x45800000, v38
	v_cndmask_b32_e64 v38, v38, v39, s[42:43]
	v_mul_f32_e32 v38, v143, v38
	v_cndmask_b32_e64 v38, v38, 1.0, s[50:51]
	v_pk_mul_f32 v[40:41], v[32:33], v[38:39] op_sel_hi:[1,0]
	v_pk_mul_f32 v[42:43], v[30:31], v[38:39] op_sel_hi:[1,0]
	global_load_dwordx4 v[176:179], v[138:139], off
	v_pk_mul_f32 v[48:49], v[26:27], v[38:39] op_sel_hi:[1,0]
	v_pk_mul_f32 v[50:51], v[28:29], v[38:39] op_sel_hi:[1,0]
	s_waitcnt vmcnt(12)
	v_pk_mul_f32 v[44:45], v[42:43], v[188:189]
	v_pk_mul_f32 v[46:47], v[40:41], v[190:191]
	v_cndmask_b32_e64 v251, v87, v71, s[40:41]
	v_lshlrev_b32_e32 v251, 4, v251
	v_cndmask_b32_e32 v251, 0, v251, vcc
	v_lshlrev_b32_e32 v251, 2, v251
	global_load_dwordx4 v[180:183], v251, s[22:23]
	global_load_dwordx4 v[184:187], v251, s[22:23] offset:16
	global_load_dwordx4 v[188:191], v[140:141], off
	s_waitcnt vmcnt(13)
	v_mov_b32_e32 v52, v196
	s_waitcnt vmcnt(12)
	v_pk_mul_f32 v[28:29], v[50:51], v[206:207]
	v_pk_mul_f32 v[26:27], v[48:49], v[204:205]
	v_mov_b32_e32 v48, v192
	v_mov_b32_e32 v49, v194
	v_mov_b32_e32 v53, v198
	v_mov_b32_e32 v198, v197
	v_mov_b32_e32 v194, v193
	v_pk_mul_f32 v[50:51], v[48:49], v[26:27]
	v_pk_mul_f32 v[54:55], v[52:53], v[28:29]
	v_pk_mul_f32 v[26:27], v[194:195], v[26:27]
	v_pk_mul_f32 v[28:29], v[198:199], v[28:29]
	v_pk_fma_f32 v[26:27], v[44:45], v[48:49], v[26:27] neg_lo:[0,0,1] neg_hi:[0,0,1]
	v_pk_fma_f32 v[28:29], v[46:47], v[52:53], v[28:29] neg_lo:[0,0,1] neg_hi:[0,0,1]
	v_pk_fma_f32 v[40:41], v[46:47], v[198:199], v[54:55]
	v_pk_fma_f32 v[30:31], v[44:45], v[194:195], v[50:51]
	v_cvt_pk_bf16_f32 v26, v26, v27
	v_cvt_pk_bf16_f32 v27, v28, v29
	global_store_dwordx2 v[36:37], v[26:27], off
	v_cvt_pk_bf16_f32 v26, v30, v31
	v_cvt_pk_bf16_f32 v27, v40, v41
	global_store_dwordx2 v[34:35], v[26:27], off
	v_pk_mul_f32 v[26:27], v[24:25], v[38:39] op_sel_hi:[1,0]
	v_pk_mul_f32 v[28:29], v[22:23], v[38:39] op_sel_hi:[1,0]
	global_load_dwordx4 v[192:195], v[138:139], off offset:16
	v_pk_mul_f32 v[40:41], v[18:19], v[38:39] op_sel_hi:[1,0]
	s_waitcnt vmcnt(12)
	v_pk_mul_f32 v[30:31], v[28:29], v[200:201]
	v_pk_mul_f32 v[32:33], v[26:27], v[202:203]
	global_load_dwordx4 v[196:199], v251, s[22:23] offset:32
	global_load_dwordx4 v[200:203], v251, s[22:23] offset:48
	v_pk_mul_f32 v[38:39], v[20:21], v[38:39] op_sel_hi:[1,0]
	global_load_dwordx4 v[204:207], v[140:141], off offset:16
	s_waitcnt vmcnt(13)
	v_mov_b32_e32 v42, v212
	v_mov_b32_e32 v43, v214
	s_waitcnt vmcnt(12)
	v_pk_mul_f32 v[20:21], v[38:39], v[226:227]
	v_pk_mul_f32 v[18:19], v[40:41], v[224:225]
	v_mov_b32_e32 v38, v172
	v_mov_b32_e32 v39, v174
	v_mov_b32_e32 v214, v213
	v_mov_b32_e32 v174, v173
	v_pk_mul_f32 v[40:41], v[38:39], v[18:19]
	v_pk_mul_f32 v[44:45], v[42:43], v[20:21]
	v_pk_mul_f32 v[18:19], v[174:175], v[18:19]
	v_pk_mul_f32 v[20:21], v[214:215], v[20:21]
	v_pk_fma_f32 v[18:19], v[30:31], v[38:39], v[18:19] neg_lo:[0,0,1] neg_hi:[0,0,1]
	v_pk_fma_f32 v[20:21], v[32:33], v[42:43], v[20:21] neg_lo:[0,0,1] neg_hi:[0,0,1]
	v_pk_fma_f32 v[26:27], v[32:33], v[214:215], v[44:45]
	v_pk_fma_f32 v[22:23], v[30:31], v[174:175], v[40:41]
	v_cvt_pk_bf16_f32 v18, v18, v19
	v_cvt_pk_bf16_f32 v19, v20, v21
	global_store_dwordx2 v[36:37], v[18:19], off offset:8
	v_cvt_pk_bf16_f32 v18, v22, v23
	v_cvt_pk_bf16_f32 v19, v26, v27
	global_store_dwordx2 v[34:35], v[18:19], off offset:8
; template <int K> __device__ __forceinline__ float swz(float v) { return __int_as_float(__builtin_amdgcn_ds_swizzle(__float_as_int(v), (K << 10) | 0x1f)); }
; __device__ __forceinline__ float x32_sum(float v) { auto r = __builtin_amdgcn_permlane32_swap(__float_as_uint(v), __float_as_uint(v), false, false); return __uint_as_float(r[0]) + __uint_as_float(r[1]); }
; __device__ __forceinline__ unsigned cvt_pk_bf16(float lo, float hi) { const f32x2c f = {lo, hi}; return __builtin_bit_cast(unsigned, __builtin_convertvector(f, bf16x2c)); }
;     __device__ __forceinline__ void operator()(const f32x4 (&acc)[2][2][4][2], const Unit& u, int wr, int wc, int, int) const {
;     ...
;             for (int m = 0; m < 4; ++m) {
;                 const int row = rowb + ai * HALF + m * 16;
;                 float ss = 0.f;
; #pragma unroll
;                 for (int j = 0; j < 4; ++j) ss += acc[ai][0][m][0][j] * acc[ai][0][m][0][j] + acc[ai][0][m][1][j] * acc[ai][0][m][1][j] + acc[ai][1][m][0][j] * acc[ai][1][m][0][j] + acc[ai][1][m][1][j] * acc[ai][1][m][1][j];
;                 ss += ::swz<16>(ss); ss = ::x32_sum(ss);
;                 float rs = rsqrtf(ss * inv_cnt + 1e-6f) * sc; rs = is_v ? 1.0f : rs;
;                 const int pos = row & 2047, pp = rot ? ((fq & 1) ? (pos & 63) : (pos >> 6)) : 0;
;                 const float* rt = rope + pp * 16;
;                 bf16_t* dst = obase + (unsigned)(row * ostride + ocol);
; #pragma unroll
;                 for (int n = 0; n < 2; ++n) {
;                     const f32x4 g1 = *(const f32x4*)(g + 4 * n), g2 = *(const f32x4*)(g + sbj + 4 * n);
;                     const f32x4 t0 = *(const f32x4*)(rt + 8 * n), t1 = *(const f32x4*)(rt + 8 * n + 4);
;                     const f32x4 c = (f32x4){t0[0], t0[2], t1[0], t1[2]}, s = (f32x4){t0[1], t0[3], t1[1], t1[3]};
;                     const f32x4 a1 = acc[ai][0][m][n] * rs * g1, a2 = acc[ai][1][m][n] * rs * g2;
;                     const f32x4 o1 = a1 * c - a2 * s, o2 = a1 * s + a2 * c;
;                     if (st_ok) { u32x2 w; w.x = cvt_pk_bf16(o1[0], o1[1]); w.y = cvt_pk_bf16(o1[2], o1[3]); *(u32x2*)(dst + 4 * n) = w;
;                         w.x = cvt_pk_bf16(o2[0], o2[1]); w.y = cvt_pk_bf16(o2[2], o2[3]); *(u32x2*)(dst + sbj + 4 * n) = w; }
;                 }
;                 asm volatile("" ::: "memory");
.LBB0_683:
	s_or_b64 exec, exec, s[2:3]
	v_mul_f32_e32 v18, v6, v6
	v_mul_f32_e32 v19, v7, v7
	v_fmac_f32_e32 v18, v14, v14
	v_fmac_f32_e32 v19, v15, v15
	v_fmac_f32_e32 v18, v10, v10
	v_fmac_f32_e32 v19, v11, v11
	v_fmac_f32_e32 v18, v2, v2
	v_fmac_f32_e32 v19, v3, v3
	v_add_f32_e32 v18, v18, v19
	v_mul_f32_e32 v19, v8, v8
	v_fmac_f32_e32 v19, v16, v16
	v_fmac_f32_e32 v19, v12, v12
	v_fmac_f32_e32 v19, v4, v4
	v_add_f32_e32 v18, v19, v18
	v_mul_f32_e32 v19, v9, v9
	v_fmac_f32_e32 v19, v17, v17
	v_fmac_f32_e32 v19, v13, v13
	v_fmac_f32_e32 v19, v5, v5
	v_add_f32_e32 v18, v19, v18
	ds_swizzle_b32 v19, v18 offset:swizzle(SWAP,16)
	s_waitcnt lgkmcnt(0)
	v_add_f32_e32 v22, v18, v19
	v_mov_b32_e32 v23, v22
	s_nop 1
	v_permlane32_swap_b32_e32 v22, v23
	s_and_saveexec_b64 s[2:3], s[20:21]
	v_add_f32_e32 v22, v22, v23
	v_fmaak_f32 v22, v159, v22, 0x358637bd
	v_cmp_gt_f32_e64 s[42:43], s88, v22
	v_mul_f32_e32 v23, 0x4b800000, v22
	v_add_u32_e32 v18, 0xb0, v160
	v_cndmask_b32_e64 v22, v22, v23, s[42:43]
	v_rsq_f32_e32 v22, v22
	v_mad_u64_u32 v[18:19], s[20:21], s26, v18, v[142:143]
	v_mov_b32_e32 v19, v0
	v_mul_f32_e32 v23, 0x45800000, v22
	v_cndmask_b32_e64 v22, v22, v23, s[42:43]
	v_mul_f32_e32 v22, v143, v22
	v_cndmask_b32_e64 v22, v22, 1.0, s[50:51]
	v_pk_mul_f32 v[24:25], v[16:17], v[22:23] op_sel_hi:[1,0]
	v_pk_mul_f32 v[26:27], v[14:15], v[22:23] op_sel_hi:[1,0]
	v_pk_mul_f32 v[32:33], v[10:11], v[22:23] op_sel_hi:[1,0]
	v_pk_mul_f32 v[34:35], v[12:13], v[22:23] op_sel_hi:[1,0]
	v_lshl_add_u64 v[20:21], v[18:19], 1, s[60:61]
	s_lshl_b32 s54, s16, 1
	v_lshl_add_u64 v[18:19], v[20:21], 0, s[54:55]
	s_waitcnt vmcnt(11)
	v_pk_mul_f32 v[28:29], v[26:27], v[176:177]
	v_pk_mul_f32 v[30:31], v[24:25], v[178:179]
	s_waitcnt vmcnt(9)
	v_mov_b32_e32 v36, v184
	s_waitcnt vmcnt(8)
	v_pk_mul_f32 v[12:13], v[34:35], v[190:191]
	v_pk_mul_f32 v[10:11], v[32:33], v[188:189]
	v_mov_b32_e32 v32, v180
	v_mov_b32_e32 v33, v182
	v_mov_b32_e32 v37, v186
	v_mov_b32_e32 v186, v185
	v_mov_b32_e32 v182, v181
	v_pk_mul_f32 v[34:35], v[32:33], v[10:11]
	v_pk_mul_f32 v[38:39], v[36:37], v[12:13]
	v_pk_mul_f32 v[10:11], v[182:183], v[10:11]
	v_pk_mul_f32 v[12:13], v[186:187], v[12:13]
	v_pk_fma_f32 v[10:11], v[28:29], v[32:33], v[10:11] neg_lo:[0,0,1] neg_hi:[0,0,1]
	v_pk_fma_f32 v[12:13], v[30:31], v[36:37], v[12:13] neg_lo:[0,0,1] neg_hi:[0,0,1]
	v_pk_fma_f32 v[24:25], v[30:31], v[186:187], v[38:39]
	v_pk_fma_f32 v[14:15], v[28:29], v[182:183], v[34:35]
	v_cvt_pk_bf16_f32 v10, v10, v11
	v_cvt_pk_bf16_f32 v11, v12, v13
	global_store_dwordx2 v[20:21], v[10:11], off
	v_cvt_pk_bf16_f32 v10, v14, v15
	v_cvt_pk_bf16_f32 v11, v24, v25
	global_store_dwordx2 v[18:19], v[10:11], off
	v_pk_mul_f32 v[10:11], v[8:9], v[22:23] op_sel_hi:[1,0]
	v_pk_mul_f32 v[12:13], v[6:7], v[22:23] op_sel_hi:[1,0]
	v_pk_mul_f32 v[24:25], v[2:3], v[22:23] op_sel_hi:[1,0]
	s_waitcnt vmcnt(7)
	v_pk_mul_f32 v[14:15], v[12:13], v[192:193]
	v_pk_mul_f32 v[16:17], v[10:11], v[194:195]
	v_pk_mul_f32 v[22:23], v[4:5], v[22:23] op_sel_hi:[1,0]
	s_waitcnt vmcnt(5)
	v_mov_b32_e32 v26, v200
	v_mov_b32_e32 v27, v202
	s_waitcnt vmcnt(4)
	v_pk_mul_f32 v[4:5], v[22:23], v[206:207]
	v_pk_mul_f32 v[2:3], v[24:25], v[204:205]
	v_mov_b32_e32 v22, v196
	v_mov_b32_e32 v23, v198
	v_mov_b32_e32 v202, v201
	v_mov_b32_e32 v198, v197
	v_pk_mul_f32 v[24:25], v[22:23], v[2:3]
	v_pk_mul_f32 v[28:29], v[26:27], v[4:5]
	v_pk_mul_f32 v[2:3], v[198:199], v[2:3]
	v_pk_mul_f32 v[4:5], v[202:203], v[4:5]
	v_pk_fma_f32 v[2:3], v[14:15], v[22:23], v[2:3] neg_lo:[0,0,1] neg_hi:[0,0,1]
	v_pk_fma_f32 v[4:5], v[16:17], v[26:27], v[4:5] neg_lo:[0,0,1] neg_hi:[0,0,1]
	v_pk_fma_f32 v[10:11], v[16:17], v[202:203], v[28:29]
	v_pk_fma_f32 v[6:7], v[14:15], v[198:199], v[24:25]
	v_cvt_pk_bf16_f32 v2, v2, v3
	v_cvt_pk_bf16_f32 v3, v4, v5
	global_store_dwordx2 v[20:21], v[2:3], off offset:8
	v_cvt_pk_bf16_f32 v2, v6, v7
	v_cvt_pk_bf16_f32 v3, v10, v11
	global_store_dwordx2 v[18:19], v[2:3], off offset:8
	s_branch .LBB0_650
